# conv+silu epilogue: counted waits for the two halves of the weight loads (the first channel quad starts when its own eight vectors are in)
# baseline (speedup 1.0000x reference)
.LBB0_1187:
	v_readlane_b32 s12, v253, 21
	v_readlane_b32 s13, v253, 22
	v_readlane_b32 s18, v253, 27
	v_readlane_b32 s19, v253, 28
	v_readlane_b32 s20, v253, 29
	v_readlane_b32 s21, v253, 30
	v_readlane_b32 s22, v253, 31
	v_readlane_b32 s23, v253, 32
	v_readlane_b32 s24, v253, 33
	v_readlane_b32 s25, v253, 34
	v_readlane_b32 s26, v253, 35
	v_readlane_b32 s27, v253, 36
	s_mov_b64 s[14:15], s[2:3]
	s_mov_b64 s[16:17], s[34:35]
	v_lshl_or_b32 v176, s66, 7, v220
	v_lshlrev_b32_e32 v208, 2, v176
	s_lshl_b32 s34, s64, 8
	s_add_i32 s34, s34, s67
	s_lshr_b32 s35, s34, 4
	v_add_u32_e32 v209, s35, v217
	v_mul_u32_u24_e32 v209, 0x5800, v209
	v_add_u32_e32 v209, v209, v208
	v_or_b32_e32 v210, s34, v217
	v_mul_u32_u24_e32 v210, 0x1600, v210
	v_lshl_add_u32 v210, v176, 1, v210
	global_load_dwordx4 v[112:115], v208, s[24:25]
	global_load_dwordx4 v[116:119], v208, s[16:17]
	global_load_dwordx4 v[120:123], v208, s[30:31]
	global_load_dwordx4 v[124:127], v208, s[26:27]
	global_load_dwordx4 v[132:135], v208, s[14:15]
	global_load_dwordx4 v[136:139], v208, s[28:29]
	global_load_dwordx4 v[140:143], v208, s[40:41]
	global_load_dwordx4 v[144:147], v208, s[44:45]
	global_load_dwordx4 v[176:179], v208, s[24:25] offset:16
	global_load_dwordx4 v[180:183], v208, s[16:17] offset:16
	global_load_dwordx4 v[184:187], v208, s[30:31] offset:16
	global_load_dwordx4 v[188:191], v208, s[26:27] offset:16
	global_load_dwordx4 v[192:195], v208, s[14:15] offset:16
	global_load_dwordx4 v[196:199], v208, s[28:29] offset:16
	global_load_dwordx4 v[200:203], v208, s[40:41] offset:16
	global_load_dwordx4 v[204:207], v208, s[44:45] offset:16
	s_and_saveexec_b64 s[2:3], s[6:7]
	global_store_dwordx4 v209, v[156:159], s[38:39]
	global_store_dwordx4 v209, v[60:63], s[38:39] offset:16
	v_add_u32_e32 v211, 0x2c00, v209
	global_store_dwordx4 v211, v[152:155], s[38:39]
	global_store_dwordx4 v211, v[56:59], s[38:39] offset:16
	v_add_u32_e32 v211, 0x2c000, v209
	global_store_dwordx4 v211, v[92:95], s[38:39]
	global_store_dwordx4 v211, v[28:31], s[38:39] offset:16
	v_add_u32_e32 v211, 0x2ec00, v209
	global_store_dwordx4 v211, v[88:91], s[38:39]
	global_store_dwordx4 v211, v[24:27], s[38:39] offset:16
	s_or_b64 exec, exec, s[2:3]
	v_add_u32_e32 v212, 0xfffbe000, v209
	s_and_saveexec_b64 s[2:3], s[8:9]
	global_store_dwordx4 v212, v[100:103], s[38:39]
	global_store_dwordx4 v212, v[36:39], s[38:39] offset:16
	v_add_u32_e32 v211, 0x2c00, v212
	global_store_dwordx4 v211, v[96:99], s[38:39]
	global_store_dwordx4 v211, v[32:35], s[38:39] offset:16
	v_add_u32_e32 v211, 0x2c000, v212
	global_store_dwordx4 v211, v[68:71], s[38:39]
	global_store_dwordx4 v211, v[4:7], s[38:39] offset:16
	v_add_u32_e32 v211, 0x2ec00, v212
	global_store_dwordx4 v211, v[64:67], s[38:39]
	global_store_dwordx4 v211, v[0:3], s[38:39] offset:16
	s_or_b64 exec, exec, s[2:3]
	v_mov_b32_e32 v238, 0xbfb8aa3b
	v_mov_b32_e32 v239, 0xbfb8aa3b
	s_waitcnt vmcnt(24)
	v_pk_fma_f32 v[224:225], v[116:117], v[156:157], v[124:125]
	v_pk_fma_f32 v[226:227], v[118:119], v[158:159], v[126:127]
	v_fmac_f32_dpp v224, v156, v112 row_shr:1 row_mask:0xf bank_mask:0xf
	v_fmac_f32_dpp v225, v157, v113 row_shr:1 row_mask:0xf bank_mask:0xf
	v_fmac_f32_dpp v226, v158, v114 row_shr:1 row_mask:0xf bank_mask:0xf
	v_fmac_f32_dpp v227, v159, v115 row_shr:1 row_mask:0xf bank_mask:0xf
	v_fmac_f32_dpp v224, v156, v120 row_shl:1 row_mask:0xf bank_mask:0xf
	v_fmac_f32_dpp v225, v157, v121 row_shl:1 row_mask:0xf bank_mask:0xf
	v_fmac_f32_dpp v226, v158, v122 row_shl:1 row_mask:0xf bank_mask:0xf
	v_fmac_f32_dpp v227, v159, v123 row_shl:1 row_mask:0xf bank_mask:0xf
	v_fmac_f32_dpp v224, v148, v120 row_shr:15 row_mask:0xf bank_mask:0xf
	v_fmac_f32_dpp v225, v149, v121 row_shr:15 row_mask:0xf bank_mask:0xf
	v_fmac_f32_dpp v226, v150, v122 row_shr:15 row_mask:0xf bank_mask:0xf
	v_fmac_f32_dpp v227, v151, v123 row_shr:15 row_mask:0xf bank_mask:0xf
	v_pk_fma_f32 v[228:229], v[136:137], v[152:153], v[144:145]
	v_pk_fma_f32 v[230:231], v[138:139], v[154:155], v[146:147]
	v_fmac_f32_dpp v228, v152, v132 row_shr:1 row_mask:0xf bank_mask:0xf
	v_fmac_f32_dpp v229, v153, v133 row_shr:1 row_mask:0xf bank_mask:0xf
	v_fmac_f32_dpp v230, v154, v134 row_shr:1 row_mask:0xf bank_mask:0xf
	v_fmac_f32_dpp v231, v155, v135 row_shr:1 row_mask:0xf bank_mask:0xf
	v_fmac_f32_dpp v228, v152, v140 row_shl:1 row_mask:0xf bank_mask:0xf
	v_fmac_f32_dpp v229, v153, v141 row_shl:1 row_mask:0xf bank_mask:0xf
	v_fmac_f32_dpp v230, v154, v142 row_shl:1 row_mask:0xf bank_mask:0xf
	v_fmac_f32_dpp v231, v155, v143 row_shl:1 row_mask:0xf bank_mask:0xf
	v_fmac_f32_dpp v228, v128, v140 row_shr:15 row_mask:0xf bank_mask:0xf
	v_fmac_f32_dpp v229, v129, v141 row_shr:15 row_mask:0xf bank_mask:0xf
	v_fmac_f32_dpp v230, v130, v142 row_shr:15 row_mask:0xf bank_mask:0xf
	v_fmac_f32_dpp v231, v131, v143 row_shr:15 row_mask:0xf bank_mask:0xf
	v_pk_mul_f32 v[232:233], v[224:225], v[238:239]
	v_pk_mul_f32 v[234:235], v[226:227], v[238:239]
	v_exp_f32_e32 v232, v232
	v_exp_f32_e32 v233, v233
	v_exp_f32_e32 v234, v234
	v_exp_f32_e32 v235, v235
	v_pk_add_f32 v[232:233], v[232:233], 1.0 op_sel_hi:[1,0]
	v_pk_add_f32 v[234:235], v[234:235], 1.0 op_sel_hi:[1,0]
	v_rcp_f32_e32 v232, v232
	v_rcp_f32_e32 v233, v233
	v_rcp_f32_e32 v234, v234
	v_rcp_f32_e32 v235, v235
	v_pk_mul_f32 v[224:225], v[224:225], v[232:233]
	v_pk_mul_f32 v[226:227], v[226:227], v[234:235]
	v_pk_mul_f32 v[224:225], v[224:225], v[228:229]
	v_pk_mul_f32 v[226:227], v[226:227], v[230:231]
	v_cvt_pk_bf16_f32 v244, v224, v225
	v_cvt_pk_bf16_f32 v245, v226, v227
	s_waitcnt vmcnt(16)
	v_pk_fma_f32 v[224:225], v[180:181], v[60:61], v[188:189]
	v_pk_fma_f32 v[226:227], v[182:183], v[62:63], v[190:191]
	v_fmac_f32_dpp v224, v60, v176 row_shr:1 row_mask:0xf bank_mask:0xf
	v_fmac_f32_dpp v225, v61, v177 row_shr:1 row_mask:0xf bank_mask:0xf
	v_fmac_f32_dpp v226, v62, v178 row_shr:1 row_mask:0xf bank_mask:0xf
	v_fmac_f32_dpp v227, v63, v179 row_shr:1 row_mask:0xf bank_mask:0xf
	v_fmac_f32_dpp v224, v60, v184 row_shl:1 row_mask:0xf bank_mask:0xf
	v_fmac_f32_dpp v225, v61, v185 row_shl:1 row_mask:0xf bank_mask:0xf
	v_fmac_f32_dpp v226, v62, v186 row_shl:1 row_mask:0xf bank_mask:0xf
	v_fmac_f32_dpp v227, v63, v187 row_shl:1 row_mask:0xf bank_mask:0xf
	v_fmac_f32_dpp v224, v52, v184 row_shr:15 row_mask:0xf bank_mask:0xf
	v_fmac_f32_dpp v225, v53, v185 row_shr:15 row_mask:0xf bank_mask:0xf
	v_fmac_f32_dpp v226, v54, v186 row_shr:15 row_mask:0xf bank_mask:0xf
	v_fmac_f32_dpp v227, v55, v187 row_shr:15 row_mask:0xf bank_mask:0xf
	v_pk_fma_f32 v[228:229], v[196:197], v[56:57], v[204:205]
	v_pk_fma_f32 v[230:231], v[198:199], v[58:59], v[206:207]
	v_fmac_f32_dpp v228, v56, v192 row_shr:1 row_mask:0xf bank_mask:0xf
	v_fmac_f32_dpp v229, v57, v193 row_shr:1 row_mask:0xf bank_mask:0xf
	v_fmac_f32_dpp v230, v58, v194 row_shr:1 row_mask:0xf bank_mask:0xf
	v_fmac_f32_dpp v231, v59, v195 row_shr:1 row_mask:0xf bank_mask:0xf
	v_fmac_f32_dpp v228, v56, v200 row_shl:1 row_mask:0xf bank_mask:0xf
	v_fmac_f32_dpp v229, v57, v201 row_shl:1 row_mask:0xf bank_mask:0xf
	v_fmac_f32_dpp v230, v58, v202 row_shl:1 row_mask:0xf bank_mask:0xf
	v_fmac_f32_dpp v231, v59, v203 row_shl:1 row_mask:0xf bank_mask:0xf
	v_fmac_f32_dpp v228, v48, v200 row_shr:15 row_mask:0xf bank_mask:0xf
	v_fmac_f32_dpp v229, v49, v201 row_shr:15 row_mask:0xf bank_mask:0xf
	v_fmac_f32_dpp v230, v50, v202 row_shr:15 row_mask:0xf bank_mask:0xf
	v_fmac_f32_dpp v231, v51, v203 row_shr:15 row_mask:0xf bank_mask:0xf
	v_pk_mul_f32 v[232:233], v[224:225], v[238:239]
	v_pk_mul_f32 v[234:235], v[226:227], v[238:239]
	v_exp_f32_e32 v232, v232
	v_exp_f32_e32 v233, v233
	v_exp_f32_e32 v234, v234
	v_exp_f32_e32 v235, v235
	v_pk_add_f32 v[232:233], v[232:233], 1.0 op_sel_hi:[1,0]
	v_pk_add_f32 v[234:235], v[234:235], 1.0 op_sel_hi:[1,0]
	v_rcp_f32_e32 v232, v232
	v_rcp_f32_e32 v233, v233
	v_rcp_f32_e32 v234, v234
	v_rcp_f32_e32 v235, v235
	v_pk_mul_f32 v[224:225], v[224:225], v[232:233]
	v_pk_mul_f32 v[226:227], v[226:227], v[234:235]
	v_pk_mul_f32 v[224:225], v[224:225], v[228:229]
	v_pk_mul_f32 v[226:227], v[226:227], v[230:231]
	v_cvt_pk_bf16_f32 v246, v224, v225
	v_cvt_pk_bf16_f32 v247, v226, v227
	global_store_dwordx4 v210, v[244:247], s[36:37]
	v_pk_fma_f32 v[224:225], v[116:117], v[148:149], v[124:125]
	v_pk_fma_f32 v[226:227], v[118:119], v[150:151], v[126:127]
	v_fmac_f32_dpp v224, v148, v112 row_shr:1 row_mask:0xf bank_mask:0xf
	v_fmac_f32_dpp v225, v149, v113 row_shr:1 row_mask:0xf bank_mask:0xf
	v_fmac_f32_dpp v226, v150, v114 row_shr:1 row_mask:0xf bank_mask:0xf
	v_fmac_f32_dpp v227, v151, v115 row_shr:1 row_mask:0xf bank_mask:0xf
	v_fmac_f32_dpp v224, v156, v112 row_shl:15 row_mask:0xf bank_mask:0xf
	v_fmac_f32_dpp v225, v157, v113 row_shl:15 row_mask:0xf bank_mask:0xf
	v_fmac_f32_dpp v226, v158, v114 row_shl:15 row_mask:0xf bank_mask:0xf
	v_fmac_f32_dpp v227, v159, v115 row_shl:15 row_mask:0xf bank_mask:0xf
	v_fmac_f32_dpp v224, v148, v120 row_shl:1 row_mask:0xf bank_mask:0xf
	v_fmac_f32_dpp v225, v149, v121 row_shl:1 row_mask:0xf bank_mask:0xf
	v_fmac_f32_dpp v226, v150, v122 row_shl:1 row_mask:0xf bank_mask:0xf
	v_fmac_f32_dpp v227, v151, v123 row_shl:1 row_mask:0xf bank_mask:0xf
	v_fmac_f32_dpp v224, v108, v120 row_shr:15 row_mask:0xf bank_mask:0xf
	v_fmac_f32_dpp v225, v109, v121 row_shr:15 row_mask:0xf bank_mask:0xf
	v_fmac_f32_dpp v226, v110, v122 row_shr:15 row_mask:0xf bank_mask:0xf
	v_fmac_f32_dpp v227, v111, v123 row_shr:15 row_mask:0xf bank_mask:0xf
	v_pk_fma_f32 v[228:229], v[136:137], v[128:129], v[144:145]
	v_pk_fma_f32 v[230:231], v[138:139], v[130:131], v[146:147]
	v_fmac_f32_dpp v228, v128, v132 row_shr:1 row_mask:0xf bank_mask:0xf
	v_fmac_f32_dpp v229, v129, v133 row_shr:1 row_mask:0xf bank_mask:0xf
	v_fmac_f32_dpp v230, v130, v134 row_shr:1 row_mask:0xf bank_mask:0xf
	v_fmac_f32_dpp v231, v131, v135 row_shr:1 row_mask:0xf bank_mask:0xf
	v_fmac_f32_dpp v228, v152, v132 row_shl:15 row_mask:0xf bank_mask:0xf
	v_fmac_f32_dpp v229, v153, v133 row_shl:15 row_mask:0xf bank_mask:0xf
	v_fmac_f32_dpp v230, v154, v134 row_shl:15 row_mask:0xf bank_mask:0xf
	v_fmac_f32_dpp v231, v155, v135 row_shl:15 row_mask:0xf bank_mask:0xf
	v_fmac_f32_dpp v228, v128, v140 row_shl:1 row_mask:0xf bank_mask:0xf
	v_fmac_f32_dpp v229, v129, v141 row_shl:1 row_mask:0xf bank_mask:0xf
	v_fmac_f32_dpp v230, v130, v142 row_shl:1 row_mask:0xf bank_mask:0xf
	v_fmac_f32_dpp v231, v131, v143 row_shl:1 row_mask:0xf bank_mask:0xf
	v_fmac_f32_dpp v228, v104, v140 row_shr:15 row_mask:0xf bank_mask:0xf
	v_fmac_f32_dpp v229, v105, v141 row_shr:15 row_mask:0xf bank_mask:0xf
	v_fmac_f32_dpp v230, v106, v142 row_shr:15 row_mask:0xf bank_mask:0xf
	v_fmac_f32_dpp v231, v107, v143 row_shr:15 row_mask:0xf bank_mask:0xf
	v_pk_mul_f32 v[232:233], v[224:225], v[238:239]
	v_pk_mul_f32 v[234:235], v[226:227], v[238:239]
	v_exp_f32_e32 v232, v232
	v_exp_f32_e32 v233, v233
	v_exp_f32_e32 v234, v234
	v_exp_f32_e32 v235, v235
	v_pk_add_f32 v[232:233], v[232:233], 1.0 op_sel_hi:[1,0]
	v_pk_add_f32 v[234:235], v[234:235], 1.0 op_sel_hi:[1,0]
	v_rcp_f32_e32 v232, v232
	v_rcp_f32_e32 v233, v233
	v_rcp_f32_e32 v234, v234
	v_rcp_f32_e32 v235, v235
	v_pk_mul_f32 v[224:225], v[224:225], v[232:233]
	v_pk_mul_f32 v[226:227], v[226:227], v[234:235]
	v_pk_mul_f32 v[224:225], v[224:225], v[228:229]
	v_pk_mul_f32 v[226:227], v[226:227], v[230:231]
	v_cvt_pk_bf16_f32 v244, v224, v225
	v_cvt_pk_bf16_f32 v245, v226, v227
	v_pk_fma_f32 v[224:225], v[180:181], v[52:53], v[188:189]
	v_pk_fma_f32 v[226:227], v[182:183], v[54:55], v[190:191]
	v_fmac_f32_dpp v224, v52, v176 row_shr:1 row_mask:0xf bank_mask:0xf
	v_fmac_f32_dpp v225, v53, v177 row_shr:1 row_mask:0xf bank_mask:0xf
	v_fmac_f32_dpp v226, v54, v178 row_shr:1 row_mask:0xf bank_mask:0xf
	v_fmac_f32_dpp v227, v55, v179 row_shr:1 row_mask:0xf bank_mask:0xf
	v_fmac_f32_dpp v224, v60, v176 row_shl:15 row_mask:0xf bank_mask:0xf
	v_fmac_f32_dpp v225, v61, v177 row_shl:15 row_mask:0xf bank_mask:0xf
	v_fmac_f32_dpp v226, v62, v178 row_shl:15 row_mask:0xf bank_mask:0xf
	v_fmac_f32_dpp v227, v63, v179 row_shl:15 row_mask:0xf bank_mask:0xf
	v_fmac_f32_dpp v224, v52, v184 row_shl:1 row_mask:0xf bank_mask:0xf
	v_fmac_f32_dpp v225, v53, v185 row_shl:1 row_mask:0xf bank_mask:0xf
	v_fmac_f32_dpp v226, v54, v186 row_shl:1 row_mask:0xf bank_mask:0xf
	v_fmac_f32_dpp v227, v55, v187 row_shl:1 row_mask:0xf bank_mask:0xf
	v_fmac_f32_dpp v224, v44, v184 row_shr:15 row_mask:0xf bank_mask:0xf
	v_fmac_f32_dpp v225, v45, v185 row_shr:15 row_mask:0xf bank_mask:0xf
	v_fmac_f32_dpp v226, v46, v186 row_shr:15 row_mask:0xf bank_mask:0xf
	v_fmac_f32_dpp v227, v47, v187 row_shr:15 row_mask:0xf bank_mask:0xf
	v_pk_fma_f32 v[228:229], v[196:197], v[48:49], v[204:205]
	v_pk_fma_f32 v[230:231], v[198:199], v[50:51], v[206:207]
	v_fmac_f32_dpp v228, v48, v192 row_shr:1 row_mask:0xf bank_mask:0xf
	v_fmac_f32_dpp v229, v49, v193 row_shr:1 row_mask:0xf bank_mask:0xf
	v_fmac_f32_dpp v230, v50, v194 row_shr:1 row_mask:0xf bank_mask:0xf
	v_fmac_f32_dpp v231, v51, v195 row_shr:1 row_mask:0xf bank_mask:0xf
	v_fmac_f32_dpp v228, v56, v192 row_shl:15 row_mask:0xf bank_mask:0xf
	v_fmac_f32_dpp v229, v57, v193 row_shl:15 row_mask:0xf bank_mask:0xf
	v_fmac_f32_dpp v230, v58, v194 row_shl:15 row_mask:0xf bank_mask:0xf
	v_fmac_f32_dpp v231, v59, v195 row_shl:15 row_mask:0xf bank_mask:0xf
	v_fmac_f32_dpp v228, v48, v200 row_shl:1 row_mask:0xf bank_mask:0xf
	v_fmac_f32_dpp v229, v49, v201 row_shl:1 row_mask:0xf bank_mask:0xf
	v_fmac_f32_dpp v230, v50, v202 row_shl:1 row_mask:0xf bank_mask:0xf
	v_fmac_f32_dpp v231, v51, v203 row_shl:1 row_mask:0xf bank_mask:0xf
	v_fmac_f32_dpp v228, v40, v200 row_shr:15 row_mask:0xf bank_mask:0xf
	v_fmac_f32_dpp v229, v41, v201 row_shr:15 row_mask:0xf bank_mask:0xf
	v_fmac_f32_dpp v230, v42, v202 row_shr:15 row_mask:0xf bank_mask:0xf
	v_fmac_f32_dpp v231, v43, v203 row_shr:15 row_mask:0xf bank_mask:0xf
	v_pk_mul_f32 v[232:233], v[224:225], v[238:239]
	v_pk_mul_f32 v[234:235], v[226:227], v[238:239]
	v_exp_f32_e32 v232, v232
	v_exp_f32_e32 v233, v233
	v_exp_f32_e32 v234, v234
	v_exp_f32_e32 v235, v235
	v_pk_add_f32 v[232:233], v[232:233], 1.0 op_sel_hi:[1,0]
	v_pk_add_f32 v[234:235], v[234:235], 1.0 op_sel_hi:[1,0]
	v_rcp_f32_e32 v232, v232
	v_rcp_f32_e32 v233, v233
	v_rcp_f32_e32 v234, v234
	v_rcp_f32_e32 v235, v235
	v_pk_mul_f32 v[224:225], v[224:225], v[232:233]
	v_pk_mul_f32 v[226:227], v[226:227], v[234:235]
	v_pk_mul_f32 v[224:225], v[224:225], v[228:229]
	v_pk_mul_f32 v[226:227], v[226:227], v[230:231]
	v_cvt_pk_bf16_f32 v246, v224, v225
	v_cvt_pk_bf16_f32 v247, v226, v227
	v_add_u32_e32 v213, 0x16000, v210
	global_store_dwordx4 v213, v[244:247], s[36:37]
	v_pk_fma_f32 v[224:225], v[116:117], v[108:109], v[124:125]
	v_pk_fma_f32 v[226:227], v[118:119], v[110:111], v[126:127]
	v_fmac_f32_dpp v224, v108, v112 row_shr:1 row_mask:0xf bank_mask:0xf
	v_fmac_f32_dpp v225, v109, v113 row_shr:1 row_mask:0xf bank_mask:0xf
	v_fmac_f32_dpp v226, v110, v114 row_shr:1 row_mask:0xf bank_mask:0xf
	v_fmac_f32_dpp v227, v111, v115 row_shr:1 row_mask:0xf bank_mask:0xf
	v_fmac_f32_dpp v224, v148, v112 row_shl:15 row_mask:0xf bank_mask:0xf
	v_fmac_f32_dpp v225, v149, v113 row_shl:15 row_mask:0xf bank_mask:0xf
	v_fmac_f32_dpp v226, v150, v114 row_shl:15 row_mask:0xf bank_mask:0xf
	v_fmac_f32_dpp v227, v151, v115 row_shl:15 row_mask:0xf bank_mask:0xf
	v_fmac_f32_dpp v224, v108, v120 row_shl:1 row_mask:0xf bank_mask:0xf
	v_fmac_f32_dpp v225, v109, v121 row_shl:1 row_mask:0xf bank_mask:0xf
	v_fmac_f32_dpp v226, v110, v122 row_shl:1 row_mask:0xf bank_mask:0xf
	v_fmac_f32_dpp v227, v111, v123 row_shl:1 row_mask:0xf bank_mask:0xf
	v_fmac_f32_dpp v224, v100, v120 row_shr:15 row_mask:0xf bank_mask:0xf
	v_fmac_f32_dpp v225, v101, v121 row_shr:15 row_mask:0xf bank_mask:0xf
	v_fmac_f32_dpp v226, v102, v122 row_shr:15 row_mask:0xf bank_mask:0xf
	v_fmac_f32_dpp v227, v103, v123 row_shr:15 row_mask:0xf bank_mask:0xf
	v_pk_fma_f32 v[228:229], v[136:137], v[104:105], v[144:145]
	v_pk_fma_f32 v[230:231], v[138:139], v[106:107], v[146:147]
	v_fmac_f32_dpp v228, v104, v132 row_shr:1 row_mask:0xf bank_mask:0xf
	v_fmac_f32_dpp v229, v105, v133 row_shr:1 row_mask:0xf bank_mask:0xf
	v_fmac_f32_dpp v230, v106, v134 row_shr:1 row_mask:0xf bank_mask:0xf
	v_fmac_f32_dpp v231, v107, v135 row_shr:1 row_mask:0xf bank_mask:0xf
	v_fmac_f32_dpp v228, v128, v132 row_shl:15 row_mask:0xf bank_mask:0xf
	v_fmac_f32_dpp v229, v129, v133 row_shl:15 row_mask:0xf bank_mask:0xf
	v_fmac_f32_dpp v230, v130, v134 row_shl:15 row_mask:0xf bank_mask:0xf
	v_fmac_f32_dpp v231, v131, v135 row_shl:15 row_mask:0xf bank_mask:0xf
	v_fmac_f32_dpp v228, v104, v140 row_shl:1 row_mask:0xf bank_mask:0xf
	v_fmac_f32_dpp v229, v105, v141 row_shl:1 row_mask:0xf bank_mask:0xf
	v_fmac_f32_dpp v230, v106, v142 row_shl:1 row_mask:0xf bank_mask:0xf
	v_fmac_f32_dpp v231, v107, v143 row_shl:1 row_mask:0xf bank_mask:0xf
	v_fmac_f32_dpp v228, v96, v140 row_shr:15 row_mask:0xf bank_mask:0xf
	v_fmac_f32_dpp v229, v97, v141 row_shr:15 row_mask:0xf bank_mask:0xf
	v_fmac_f32_dpp v230, v98, v142 row_shr:15 row_mask:0xf bank_mask:0xf
	v_fmac_f32_dpp v231, v99, v143 row_shr:15 row_mask:0xf bank_mask:0xf
	v_pk_mul_f32 v[232:233], v[224:225], v[238:239]
	v_pk_mul_f32 v[234:235], v[226:227], v[238:239]
	v_exp_f32_e32 v232, v232
	v_exp_f32_e32 v233, v233
	v_exp_f32_e32 v234, v234
	v_exp_f32_e32 v235, v235
	v_pk_add_f32 v[232:233], v[232:233], 1.0 op_sel_hi:[1,0]
	v_pk_add_f32 v[234:235], v[234:235], 1.0 op_sel_hi:[1,0]
	v_rcp_f32_e32 v232, v232
	v_rcp_f32_e32 v233, v233
	v_rcp_f32_e32 v234, v234
	v_rcp_f32_e32 v235, v235
	v_pk_mul_f32 v[224:225], v[224:225], v[232:233]
	v_pk_mul_f32 v[226:227], v[226:227], v[234:235]
	v_pk_mul_f32 v[224:225], v[224:225], v[228:229]
	v_pk_mul_f32 v[226:227], v[226:227], v[230:231]
	v_cvt_pk_bf16_f32 v244, v224, v225
	v_cvt_pk_bf16_f32 v245, v226, v227
	v_pk_fma_f32 v[224:225], v[180:181], v[44:45], v[188:189]
	v_pk_fma_f32 v[226:227], v[182:183], v[46:47], v[190:191]
	v_fmac_f32_dpp v224, v44, v176 row_shr:1 row_mask:0xf bank_mask:0xf
	v_fmac_f32_dpp v225, v45, v177 row_shr:1 row_mask:0xf bank_mask:0xf
	v_fmac_f32_dpp v226, v46, v178 row_shr:1 row_mask:0xf bank_mask:0xf
	v_fmac_f32_dpp v227, v47, v179 row_shr:1 row_mask:0xf bank_mask:0xf
	v_fmac_f32_dpp v224, v52, v176 row_shl:15 row_mask:0xf bank_mask:0xf
	v_fmac_f32_dpp v225, v53, v177 row_shl:15 row_mask:0xf bank_mask:0xf
	v_fmac_f32_dpp v226, v54, v178 row_shl:15 row_mask:0xf bank_mask:0xf
	v_fmac_f32_dpp v227, v55, v179 row_shl:15 row_mask:0xf bank_mask:0xf
	v_fmac_f32_dpp v224, v44, v184 row_shl:1 row_mask:0xf bank_mask:0xf
	v_fmac_f32_dpp v225, v45, v185 row_shl:1 row_mask:0xf bank_mask:0xf
	v_fmac_f32_dpp v226, v46, v186 row_shl:1 row_mask:0xf bank_mask:0xf
	v_fmac_f32_dpp v227, v47, v187 row_shl:1 row_mask:0xf bank_mask:0xf
	v_fmac_f32_dpp v224, v36, v184 row_shr:15 row_mask:0xf bank_mask:0xf
	v_fmac_f32_dpp v225, v37, v185 row_shr:15 row_mask:0xf bank_mask:0xf
	v_fmac_f32_dpp v226, v38, v186 row_shr:15 row_mask:0xf bank_mask:0xf
	v_fmac_f32_dpp v227, v39, v187 row_shr:15 row_mask:0xf bank_mask:0xf
	v_pk_fma_f32 v[228:229], v[196:197], v[40:41], v[204:205]
	v_pk_fma_f32 v[230:231], v[198:199], v[42:43], v[206:207]
	v_fmac_f32_dpp v228, v40, v192 row_shr:1 row_mask:0xf bank_mask:0xf
	v_fmac_f32_dpp v229, v41, v193 row_shr:1 row_mask:0xf bank_mask:0xf
	v_fmac_f32_dpp v230, v42, v194 row_shr:1 row_mask:0xf bank_mask:0xf
	v_fmac_f32_dpp v231, v43, v195 row_shr:1 row_mask:0xf bank_mask:0xf
	v_fmac_f32_dpp v228, v48, v192 row_shl:15 row_mask:0xf bank_mask:0xf
	v_fmac_f32_dpp v229, v49, v193 row_shl:15 row_mask:0xf bank_mask:0xf
	v_fmac_f32_dpp v230, v50, v194 row_shl:15 row_mask:0xf bank_mask:0xf
	v_fmac_f32_dpp v231, v51, v195 row_shl:15 row_mask:0xf bank_mask:0xf
	v_fmac_f32_dpp v228, v40, v200 row_shl:1 row_mask:0xf bank_mask:0xf
	v_fmac_f32_dpp v229, v41, v201 row_shl:1 row_mask:0xf bank_mask:0xf
	v_fmac_f32_dpp v230, v42, v202 row_shl:1 row_mask:0xf bank_mask:0xf
	v_fmac_f32_dpp v231, v43, v203 row_shl:1 row_mask:0xf bank_mask:0xf
	v_fmac_f32_dpp v228, v32, v200 row_shr:15 row_mask:0xf bank_mask:0xf
	v_fmac_f32_dpp v229, v33, v201 row_shr:15 row_mask:0xf bank_mask:0xf
	v_fmac_f32_dpp v230, v34, v202 row_shr:15 row_mask:0xf bank_mask:0xf
	v_fmac_f32_dpp v231, v35, v203 row_shr:15 row_mask:0xf bank_mask:0xf
	v_pk_mul_f32 v[232:233], v[224:225], v[238:239]
	v_pk_mul_f32 v[234:235], v[226:227], v[238:239]
	v_exp_f32_e32 v232, v232
	v_exp_f32_e32 v233, v233
	v_exp_f32_e32 v234, v234
	v_exp_f32_e32 v235, v235
	v_pk_add_f32 v[232:233], v[232:233], 1.0 op_sel_hi:[1,0]
	v_pk_add_f32 v[234:235], v[234:235], 1.0 op_sel_hi:[1,0]
	v_rcp_f32_e32 v232, v232
	v_rcp_f32_e32 v233, v233
	v_rcp_f32_e32 v234, v234
	v_rcp_f32_e32 v235, v235
	v_pk_mul_f32 v[224:225], v[224:225], v[232:233]
	v_pk_mul_f32 v[226:227], v[226:227], v[234:235]
	v_pk_mul_f32 v[224:225], v[224:225], v[228:229]
	v_pk_mul_f32 v[226:227], v[226:227], v[230:231]
	v_cvt_pk_bf16_f32 v246, v224, v225
	v_cvt_pk_bf16_f32 v247, v226, v227
	v_add_u32_e32 v213, 0x2c000, v210
	global_store_dwordx4 v213, v[244:247], s[36:37]
	v_pk_fma_f32 v[224:225], v[116:117], v[100:101], v[124:125]
	v_pk_fma_f32 v[226:227], v[118:119], v[102:103], v[126:127]
	v_fmac_f32_dpp v224, v100, v112 row_shr:1 row_mask:0xf bank_mask:0xf
	v_fmac_f32_dpp v225, v101, v113 row_shr:1 row_mask:0xf bank_mask:0xf
	v_fmac_f32_dpp v226, v102, v114 row_shr:1 row_mask:0xf bank_mask:0xf
	v_fmac_f32_dpp v227, v103, v115 row_shr:1 row_mask:0xf bank_mask:0xf
	v_fmac_f32_dpp v224, v108, v112 row_shl:15 row_mask:0xf bank_mask:0xf
	v_fmac_f32_dpp v225, v109, v113 row_shl:15 row_mask:0xf bank_mask:0xf
	v_fmac_f32_dpp v226, v110, v114 row_shl:15 row_mask:0xf bank_mask:0xf
	v_fmac_f32_dpp v227, v111, v115 row_shl:15 row_mask:0xf bank_mask:0xf
	v_fmac_f32_dpp v224, v100, v120 row_shl:1 row_mask:0xf bank_mask:0xf
	v_fmac_f32_dpp v225, v101, v121 row_shl:1 row_mask:0xf bank_mask:0xf
	v_fmac_f32_dpp v226, v102, v122 row_shl:1 row_mask:0xf bank_mask:0xf
	v_fmac_f32_dpp v227, v103, v123 row_shl:1 row_mask:0xf bank_mask:0xf
	v_pk_fma_f32 v[228:229], v[136:137], v[96:97], v[144:145]
	v_pk_fma_f32 v[230:231], v[138:139], v[98:99], v[146:147]
	v_fmac_f32_dpp v228, v96, v132 row_shr:1 row_mask:0xf bank_mask:0xf
	v_fmac_f32_dpp v229, v97, v133 row_shr:1 row_mask:0xf bank_mask:0xf
	v_fmac_f32_dpp v230, v98, v134 row_shr:1 row_mask:0xf bank_mask:0xf
	v_fmac_f32_dpp v231, v99, v135 row_shr:1 row_mask:0xf bank_mask:0xf
	v_fmac_f32_dpp v228, v104, v132 row_shl:15 row_mask:0xf bank_mask:0xf
	v_fmac_f32_dpp v229, v105, v133 row_shl:15 row_mask:0xf bank_mask:0xf
	v_fmac_f32_dpp v230, v106, v134 row_shl:15 row_mask:0xf bank_mask:0xf
	v_fmac_f32_dpp v231, v107, v135 row_shl:15 row_mask:0xf bank_mask:0xf
	v_fmac_f32_dpp v228, v96, v140 row_shl:1 row_mask:0xf bank_mask:0xf
	v_fmac_f32_dpp v229, v97, v141 row_shl:1 row_mask:0xf bank_mask:0xf
	v_fmac_f32_dpp v230, v98, v142 row_shl:1 row_mask:0xf bank_mask:0xf
	v_fmac_f32_dpp v231, v99, v143 row_shl:1 row_mask:0xf bank_mask:0xf
	v_pk_mul_f32 v[232:233], v[224:225], v[238:239]
	v_pk_mul_f32 v[234:235], v[226:227], v[238:239]
	v_exp_f32_e32 v232, v232
	v_exp_f32_e32 v233, v233
	v_exp_f32_e32 v234, v234
	v_exp_f32_e32 v235, v235
	v_pk_add_f32 v[232:233], v[232:233], 1.0 op_sel_hi:[1,0]
	v_pk_add_f32 v[234:235], v[234:235], 1.0 op_sel_hi:[1,0]
	v_rcp_f32_e32 v232, v232
	v_rcp_f32_e32 v233, v233
	v_rcp_f32_e32 v234, v234
	v_rcp_f32_e32 v235, v235
	v_pk_mul_f32 v[224:225], v[224:225], v[232:233]
	v_pk_mul_f32 v[226:227], v[226:227], v[234:235]
	v_pk_mul_f32 v[224:225], v[224:225], v[228:229]
	v_pk_mul_f32 v[226:227], v[226:227], v[230:231]
	v_cvt_pk_bf16_f32 v244, v224, v225
	v_cvt_pk_bf16_f32 v245, v226, v227
	v_pk_fma_f32 v[224:225], v[180:181], v[36:37], v[188:189]
	v_pk_fma_f32 v[226:227], v[182:183], v[38:39], v[190:191]
	v_fmac_f32_dpp v224, v36, v176 row_shr:1 row_mask:0xf bank_mask:0xf
	v_fmac_f32_dpp v225, v37, v177 row_shr:1 row_mask:0xf bank_mask:0xf
	v_fmac_f32_dpp v226, v38, v178 row_shr:1 row_mask:0xf bank_mask:0xf
	v_fmac_f32_dpp v227, v39, v179 row_shr:1 row_mask:0xf bank_mask:0xf
	v_fmac_f32_dpp v224, v44, v176 row_shl:15 row_mask:0xf bank_mask:0xf
	v_fmac_f32_dpp v225, v45, v177 row_shl:15 row_mask:0xf bank_mask:0xf
	v_fmac_f32_dpp v226, v46, v178 row_shl:15 row_mask:0xf bank_mask:0xf
	v_fmac_f32_dpp v227, v47, v179 row_shl:15 row_mask:0xf bank_mask:0xf
	v_fmac_f32_dpp v224, v36, v184 row_shl:1 row_mask:0xf bank_mask:0xf
	v_fmac_f32_dpp v225, v37, v185 row_shl:1 row_mask:0xf bank_mask:0xf
	v_fmac_f32_dpp v226, v38, v186 row_shl:1 row_mask:0xf bank_mask:0xf
	v_fmac_f32_dpp v227, v39, v187 row_shl:1 row_mask:0xf bank_mask:0xf
	v_pk_fma_f32 v[228:229], v[196:197], v[32:33], v[204:205]
	v_pk_fma_f32 v[230:231], v[198:199], v[34:35], v[206:207]
	v_fmac_f32_dpp v228, v32, v192 row_shr:1 row_mask:0xf bank_mask:0xf
	v_fmac_f32_dpp v229, v33, v193 row_shr:1 row_mask:0xf bank_mask:0xf
	v_fmac_f32_dpp v230, v34, v194 row_shr:1 row_mask:0xf bank_mask:0xf
	v_fmac_f32_dpp v231, v35, v195 row_shr:1 row_mask:0xf bank_mask:0xf
	v_fmac_f32_dpp v228, v40, v192 row_shl:15 row_mask:0xf bank_mask:0xf
	v_fmac_f32_dpp v229, v41, v193 row_shl:15 row_mask:0xf bank_mask:0xf
	v_fmac_f32_dpp v230, v42, v194 row_shl:15 row_mask:0xf bank_mask:0xf
	v_fmac_f32_dpp v231, v43, v195 row_shl:15 row_mask:0xf bank_mask:0xf
	v_fmac_f32_dpp v228, v32, v200 row_shl:1 row_mask:0xf bank_mask:0xf
	v_fmac_f32_dpp v229, v33, v201 row_shl:1 row_mask:0xf bank_mask:0xf
	v_fmac_f32_dpp v230, v34, v202 row_shl:1 row_mask:0xf bank_mask:0xf
	v_fmac_f32_dpp v231, v35, v203 row_shl:1 row_mask:0xf bank_mask:0xf
	v_pk_mul_f32 v[232:233], v[224:225], v[238:239]
	v_pk_mul_f32 v[234:235], v[226:227], v[238:239]
	v_exp_f32_e32 v232, v232
	v_exp_f32_e32 v233, v233
	v_exp_f32_e32 v234, v234
	v_exp_f32_e32 v235, v235
	v_pk_add_f32 v[232:233], v[232:233], 1.0 op_sel_hi:[1,0]
	v_pk_add_f32 v[234:235], v[234:235], 1.0 op_sel_hi:[1,0]
	v_rcp_f32_e32 v232, v232
	v_rcp_f32_e32 v233, v233
	v_rcp_f32_e32 v234, v234
	v_rcp_f32_e32 v235, v235
	v_pk_mul_f32 v[224:225], v[224:225], v[232:233]
	v_pk_mul_f32 v[226:227], v[226:227], v[234:235]
	v_pk_mul_f32 v[224:225], v[224:225], v[228:229]
	v_pk_mul_f32 v[226:227], v[226:227], v[230:231]
	v_cvt_pk_bf16_f32 v246, v224, v225
	v_cvt_pk_bf16_f32 v247, v226, v227
	v_add_u32_e32 v213, 0x42000, v210
	global_store_dwordx4 v213, v[244:247], s[36:37]
	v_pk_fma_f32 v[224:225], v[116:117], v[92:93], v[124:125]
	v_pk_fma_f32 v[226:227], v[118:119], v[94:95], v[126:127]
	v_fmac_f32_dpp v224, v92, v112 row_shr:1 row_mask:0xf bank_mask:0xf
	v_fmac_f32_dpp v225, v93, v113 row_shr:1 row_mask:0xf bank_mask:0xf
	v_fmac_f32_dpp v226, v94, v114 row_shr:1 row_mask:0xf bank_mask:0xf
	v_fmac_f32_dpp v227, v95, v115 row_shr:1 row_mask:0xf bank_mask:0xf
	v_fmac_f32_dpp v224, v92, v120 row_shl:1 row_mask:0xf bank_mask:0xf
	v_fmac_f32_dpp v225, v93, v121 row_shl:1 row_mask:0xf bank_mask:0xf
	v_fmac_f32_dpp v226, v94, v122 row_shl:1 row_mask:0xf bank_mask:0xf
	v_fmac_f32_dpp v227, v95, v123 row_shl:1 row_mask:0xf bank_mask:0xf
	v_fmac_f32_dpp v224, v84, v120 row_shr:15 row_mask:0xf bank_mask:0xf
	v_fmac_f32_dpp v225, v85, v121 row_shr:15 row_mask:0xf bank_mask:0xf
	v_fmac_f32_dpp v226, v86, v122 row_shr:15 row_mask:0xf bank_mask:0xf
	v_fmac_f32_dpp v227, v87, v123 row_shr:15 row_mask:0xf bank_mask:0xf
	v_pk_fma_f32 v[228:229], v[136:137], v[88:89], v[144:145]
	v_pk_fma_f32 v[230:231], v[138:139], v[90:91], v[146:147]
	v_fmac_f32_dpp v228, v88, v132 row_shr:1 row_mask:0xf bank_mask:0xf
	v_fmac_f32_dpp v229, v89, v133 row_shr:1 row_mask:0xf bank_mask:0xf
	v_fmac_f32_dpp v230, v90, v134 row_shr:1 row_mask:0xf bank_mask:0xf
	v_fmac_f32_dpp v231, v91, v135 row_shr:1 row_mask:0xf bank_mask:0xf
	v_fmac_f32_dpp v228, v88, v140 row_shl:1 row_mask:0xf bank_mask:0xf
	v_fmac_f32_dpp v229, v89, v141 row_shl:1 row_mask:0xf bank_mask:0xf
	v_fmac_f32_dpp v230, v90, v142 row_shl:1 row_mask:0xf bank_mask:0xf
	v_fmac_f32_dpp v231, v91, v143 row_shl:1 row_mask:0xf bank_mask:0xf
	v_fmac_f32_dpp v228, v80, v140 row_shr:15 row_mask:0xf bank_mask:0xf
	v_fmac_f32_dpp v229, v81, v141 row_shr:15 row_mask:0xf bank_mask:0xf
	v_fmac_f32_dpp v230, v82, v142 row_shr:15 row_mask:0xf bank_mask:0xf
	v_fmac_f32_dpp v231, v83, v143 row_shr:15 row_mask:0xf bank_mask:0xf
	v_pk_mul_f32 v[232:233], v[224:225], v[238:239]
	v_pk_mul_f32 v[234:235], v[226:227], v[238:239]
	v_exp_f32_e32 v232, v232
	v_exp_f32_e32 v233, v233
	v_exp_f32_e32 v234, v234
	v_exp_f32_e32 v235, v235
	v_pk_add_f32 v[232:233], v[232:233], 1.0 op_sel_hi:[1,0]
	v_pk_add_f32 v[234:235], v[234:235], 1.0 op_sel_hi:[1,0]
	v_rcp_f32_e32 v232, v232
	v_rcp_f32_e32 v233, v233
	v_rcp_f32_e32 v234, v234
	v_rcp_f32_e32 v235, v235
	v_pk_mul_f32 v[224:225], v[224:225], v[232:233]
	v_pk_mul_f32 v[226:227], v[226:227], v[234:235]
	v_pk_mul_f32 v[224:225], v[224:225], v[228:229]
	v_pk_mul_f32 v[226:227], v[226:227], v[230:231]
	v_cvt_pk_bf16_f32 v244, v224, v225
	v_cvt_pk_bf16_f32 v245, v226, v227
	v_pk_fma_f32 v[224:225], v[180:181], v[28:29], v[188:189]
	v_pk_fma_f32 v[226:227], v[182:183], v[30:31], v[190:191]
	v_fmac_f32_dpp v224, v28, v176 row_shr:1 row_mask:0xf bank_mask:0xf
	v_fmac_f32_dpp v225, v29, v177 row_shr:1 row_mask:0xf bank_mask:0xf
	v_fmac_f32_dpp v226, v30, v178 row_shr:1 row_mask:0xf bank_mask:0xf
	v_fmac_f32_dpp v227, v31, v179 row_shr:1 row_mask:0xf bank_mask:0xf
	v_fmac_f32_dpp v224, v28, v184 row_shl:1 row_mask:0xf bank_mask:0xf
	v_fmac_f32_dpp v225, v29, v185 row_shl:1 row_mask:0xf bank_mask:0xf
	v_fmac_f32_dpp v226, v30, v186 row_shl:1 row_mask:0xf bank_mask:0xf
	v_fmac_f32_dpp v227, v31, v187 row_shl:1 row_mask:0xf bank_mask:0xf
	v_fmac_f32_dpp v224, v20, v184 row_shr:15 row_mask:0xf bank_mask:0xf
	v_fmac_f32_dpp v225, v21, v185 row_shr:15 row_mask:0xf bank_mask:0xf
	v_fmac_f32_dpp v226, v22, v186 row_shr:15 row_mask:0xf bank_mask:0xf
	v_fmac_f32_dpp v227, v23, v187 row_shr:15 row_mask:0xf bank_mask:0xf
	v_pk_fma_f32 v[228:229], v[196:197], v[24:25], v[204:205]
	v_pk_fma_f32 v[230:231], v[198:199], v[26:27], v[206:207]
	v_fmac_f32_dpp v228, v24, v192 row_shr:1 row_mask:0xf bank_mask:0xf
	v_fmac_f32_dpp v229, v25, v193 row_shr:1 row_mask:0xf bank_mask:0xf
	v_fmac_f32_dpp v230, v26, v194 row_shr:1 row_mask:0xf bank_mask:0xf
	v_fmac_f32_dpp v231, v27, v195 row_shr:1 row_mask:0xf bank_mask:0xf
	v_fmac_f32_dpp v228, v24, v200 row_shl:1 row_mask:0xf bank_mask:0xf
	v_fmac_f32_dpp v229, v25, v201 row_shl:1 row_mask:0xf bank_mask:0xf
	v_fmac_f32_dpp v230, v26, v202 row_shl:1 row_mask:0xf bank_mask:0xf
	v_fmac_f32_dpp v231, v27, v203 row_shl:1 row_mask:0xf bank_mask:0xf
	v_fmac_f32_dpp v228, v16, v200 row_shr:15 row_mask:0xf bank_mask:0xf
	v_fmac_f32_dpp v229, v17, v201 row_shr:15 row_mask:0xf bank_mask:0xf
	v_fmac_f32_dpp v230, v18, v202 row_shr:15 row_mask:0xf bank_mask:0xf
	v_fmac_f32_dpp v231, v19, v203 row_shr:15 row_mask:0xf bank_mask:0xf
	v_pk_mul_f32 v[232:233], v[224:225], v[238:239]
	v_pk_mul_f32 v[234:235], v[226:227], v[238:239]
	v_exp_f32_e32 v232, v232
	v_exp_f32_e32 v233, v233
	v_exp_f32_e32 v234, v234
	v_exp_f32_e32 v235, v235
	v_pk_add_f32 v[232:233], v[232:233], 1.0 op_sel_hi:[1,0]
	v_pk_add_f32 v[234:235], v[234:235], 1.0 op_sel_hi:[1,0]
	v_rcp_f32_e32 v232, v232
	v_rcp_f32_e32 v233, v233
	v_rcp_f32_e32 v234, v234
	v_rcp_f32_e32 v235, v235
	v_pk_mul_f32 v[224:225], v[224:225], v[232:233]
	v_pk_mul_f32 v[226:227], v[226:227], v[234:235]
	v_pk_mul_f32 v[224:225], v[224:225], v[228:229]
	v_pk_mul_f32 v[226:227], v[226:227], v[230:231]
	v_cvt_pk_bf16_f32 v246, v224, v225
	v_cvt_pk_bf16_f32 v247, v226, v227
	v_add_u32_e32 v213, 0xb0000, v210
	global_store_dwordx4 v213, v[244:247], s[36:37]
	v_pk_fma_f32 v[224:225], v[116:117], v[84:85], v[124:125]
	v_pk_fma_f32 v[226:227], v[118:119], v[86:87], v[126:127]
	v_fmac_f32_dpp v224, v84, v112 row_shr:1 row_mask:0xf bank_mask:0xf
	v_fmac_f32_dpp v225, v85, v113 row_shr:1 row_mask:0xf bank_mask:0xf
	v_fmac_f32_dpp v226, v86, v114 row_shr:1 row_mask:0xf bank_mask:0xf
	v_fmac_f32_dpp v227, v87, v115 row_shr:1 row_mask:0xf bank_mask:0xf
	v_fmac_f32_dpp v224, v92, v112 row_shl:15 row_mask:0xf bank_mask:0xf
	v_fmac_f32_dpp v225, v93, v113 row_shl:15 row_mask:0xf bank_mask:0xf
	v_fmac_f32_dpp v226, v94, v114 row_shl:15 row_mask:0xf bank_mask:0xf
	v_fmac_f32_dpp v227, v95, v115 row_shl:15 row_mask:0xf bank_mask:0xf
	v_fmac_f32_dpp v224, v84, v120 row_shl:1 row_mask:0xf bank_mask:0xf
	v_fmac_f32_dpp v225, v85, v121 row_shl:1 row_mask:0xf bank_mask:0xf
	v_fmac_f32_dpp v226, v86, v122 row_shl:1 row_mask:0xf bank_mask:0xf
	v_fmac_f32_dpp v227, v87, v123 row_shl:1 row_mask:0xf bank_mask:0xf
	v_fmac_f32_dpp v224, v76, v120 row_shr:15 row_mask:0xf bank_mask:0xf
	v_fmac_f32_dpp v225, v77, v121 row_shr:15 row_mask:0xf bank_mask:0xf
	v_fmac_f32_dpp v226, v78, v122 row_shr:15 row_mask:0xf bank_mask:0xf
	v_fmac_f32_dpp v227, v79, v123 row_shr:15 row_mask:0xf bank_mask:0xf
	v_pk_fma_f32 v[228:229], v[136:137], v[80:81], v[144:145]
	v_pk_fma_f32 v[230:231], v[138:139], v[82:83], v[146:147]
	v_fmac_f32_dpp v228, v80, v132 row_shr:1 row_mask:0xf bank_mask:0xf
	v_fmac_f32_dpp v229, v81, v133 row_shr:1 row_mask:0xf bank_mask:0xf
	v_fmac_f32_dpp v230, v82, v134 row_shr:1 row_mask:0xf bank_mask:0xf
	v_fmac_f32_dpp v231, v83, v135 row_shr:1 row_mask:0xf bank_mask:0xf
	v_fmac_f32_dpp v228, v88, v132 row_shl:15 row_mask:0xf bank_mask:0xf
	v_fmac_f32_dpp v229, v89, v133 row_shl:15 row_mask:0xf bank_mask:0xf
	v_fmac_f32_dpp v230, v90, v134 row_shl:15 row_mask:0xf bank_mask:0xf
	v_fmac_f32_dpp v231, v91, v135 row_shl:15 row_mask:0xf bank_mask:0xf
	v_fmac_f32_dpp v228, v80, v140 row_shl:1 row_mask:0xf bank_mask:0xf
	v_fmac_f32_dpp v229, v81, v141 row_shl:1 row_mask:0xf bank_mask:0xf
	v_fmac_f32_dpp v230, v82, v142 row_shl:1 row_mask:0xf bank_mask:0xf
	v_fmac_f32_dpp v231, v83, v143 row_shl:1 row_mask:0xf bank_mask:0xf
	v_fmac_f32_dpp v228, v72, v140 row_shr:15 row_mask:0xf bank_mask:0xf
	v_fmac_f32_dpp v229, v73, v141 row_shr:15 row_mask:0xf bank_mask:0xf
	v_fmac_f32_dpp v230, v74, v142 row_shr:15 row_mask:0xf bank_mask:0xf
	v_fmac_f32_dpp v231, v75, v143 row_shr:15 row_mask:0xf bank_mask:0xf
	v_pk_mul_f32 v[232:233], v[224:225], v[238:239]
	v_pk_mul_f32 v[234:235], v[226:227], v[238:239]
	v_exp_f32_e32 v232, v232
	v_exp_f32_e32 v233, v233
	v_exp_f32_e32 v234, v234
	v_exp_f32_e32 v235, v235
	v_pk_add_f32 v[232:233], v[232:233], 1.0 op_sel_hi:[1,0]
	v_pk_add_f32 v[234:235], v[234:235], 1.0 op_sel_hi:[1,0]
	v_rcp_f32_e32 v232, v232
	v_rcp_f32_e32 v233, v233
	v_rcp_f32_e32 v234, v234
	v_rcp_f32_e32 v235, v235
	v_pk_mul_f32 v[224:225], v[224:225], v[232:233]
	v_pk_mul_f32 v[226:227], v[226:227], v[234:235]
	v_pk_mul_f32 v[224:225], v[224:225], v[228:229]
	v_pk_mul_f32 v[226:227], v[226:227], v[230:231]
	v_cvt_pk_bf16_f32 v244, v224, v225
	v_cvt_pk_bf16_f32 v245, v226, v227
	v_pk_fma_f32 v[224:225], v[180:181], v[20:21], v[188:189]
	v_pk_fma_f32 v[226:227], v[182:183], v[22:23], v[190:191]
	v_fmac_f32_dpp v224, v20, v176 row_shr:1 row_mask:0xf bank_mask:0xf
	v_fmac_f32_dpp v225, v21, v177 row_shr:1 row_mask:0xf bank_mask:0xf
	v_fmac_f32_dpp v226, v22, v178 row_shr:1 row_mask:0xf bank_mask:0xf
	v_fmac_f32_dpp v227, v23, v179 row_shr:1 row_mask:0xf bank_mask:0xf
	v_fmac_f32_dpp v224, v28, v176 row_shl:15 row_mask:0xf bank_mask:0xf
	v_fmac_f32_dpp v225, v29, v177 row_shl:15 row_mask:0xf bank_mask:0xf
	v_fmac_f32_dpp v226, v30, v178 row_shl:15 row_mask:0xf bank_mask:0xf
	v_fmac_f32_dpp v227, v31, v179 row_shl:15 row_mask:0xf bank_mask:0xf
	v_fmac_f32_dpp v224, v20, v184 row_shl:1 row_mask:0xf bank_mask:0xf
	v_fmac_f32_dpp v225, v21, v185 row_shl:1 row_mask:0xf bank_mask:0xf
	v_fmac_f32_dpp v226, v22, v186 row_shl:1 row_mask:0xf bank_mask:0xf
	v_fmac_f32_dpp v227, v23, v187 row_shl:1 row_mask:0xf bank_mask:0xf
	v_fmac_f32_dpp v224, v12, v184 row_shr:15 row_mask:0xf bank_mask:0xf
	v_fmac_f32_dpp v225, v13, v185 row_shr:15 row_mask:0xf bank_mask:0xf
	v_fmac_f32_dpp v226, v14, v186 row_shr:15 row_mask:0xf bank_mask:0xf
	v_fmac_f32_dpp v227, v15, v187 row_shr:15 row_mask:0xf bank_mask:0xf
	v_pk_fma_f32 v[228:229], v[196:197], v[16:17], v[204:205]
	v_pk_fma_f32 v[230:231], v[198:199], v[18:19], v[206:207]
	v_fmac_f32_dpp v228, v16, v192 row_shr:1 row_mask:0xf bank_mask:0xf
	v_fmac_f32_dpp v229, v17, v193 row_shr:1 row_mask:0xf bank_mask:0xf
	v_fmac_f32_dpp v230, v18, v194 row_shr:1 row_mask:0xf bank_mask:0xf
	v_fmac_f32_dpp v231, v19, v195 row_shr:1 row_mask:0xf bank_mask:0xf
	v_fmac_f32_dpp v228, v24, v192 row_shl:15 row_mask:0xf bank_mask:0xf
	v_fmac_f32_dpp v229, v25, v193 row_shl:15 row_mask:0xf bank_mask:0xf
	v_fmac_f32_dpp v230, v26, v194 row_shl:15 row_mask:0xf bank_mask:0xf
	v_fmac_f32_dpp v231, v27, v195 row_shl:15 row_mask:0xf bank_mask:0xf
	v_fmac_f32_dpp v228, v16, v200 row_shl:1 row_mask:0xf bank_mask:0xf
	v_fmac_f32_dpp v229, v17, v201 row_shl:1 row_mask:0xf bank_mask:0xf
	v_fmac_f32_dpp v230, v18, v202 row_shl:1 row_mask:0xf bank_mask:0xf
	v_fmac_f32_dpp v231, v19, v203 row_shl:1 row_mask:0xf bank_mask:0xf
	v_fmac_f32_dpp v228, v8, v200 row_shr:15 row_mask:0xf bank_mask:0xf
	v_fmac_f32_dpp v229, v9, v201 row_shr:15 row_mask:0xf bank_mask:0xf
	v_fmac_f32_dpp v230, v10, v202 row_shr:15 row_mask:0xf bank_mask:0xf
	v_fmac_f32_dpp v231, v11, v203 row_shr:15 row_mask:0xf bank_mask:0xf
	v_pk_mul_f32 v[232:233], v[224:225], v[238:239]
	v_pk_mul_f32 v[234:235], v[226:227], v[238:239]
	v_exp_f32_e32 v232, v232
	v_exp_f32_e32 v233, v233
	v_exp_f32_e32 v234, v234
	v_exp_f32_e32 v235, v235
	v_pk_add_f32 v[232:233], v[232:233], 1.0 op_sel_hi:[1,0]
	v_pk_add_f32 v[234:235], v[234:235], 1.0 op_sel_hi:[1,0]
	v_rcp_f32_e32 v232, v232
	v_rcp_f32_e32 v233, v233
	v_rcp_f32_e32 v234, v234
	v_rcp_f32_e32 v235, v235
	v_pk_mul_f32 v[224:225], v[224:225], v[232:233]
	v_pk_mul_f32 v[226:227], v[226:227], v[234:235]
	v_pk_mul_f32 v[224:225], v[224:225], v[228:229]
	v_pk_mul_f32 v[226:227], v[226:227], v[230:231]
	v_cvt_pk_bf16_f32 v246, v224, v225
	v_cvt_pk_bf16_f32 v247, v226, v227
	v_add_u32_e32 v213, 0xc6000, v210
	global_store_dwordx4 v213, v[244:247], s[36:37]
	v_pk_fma_f32 v[224:225], v[116:117], v[76:77], v[124:125]
	v_pk_fma_f32 v[226:227], v[118:119], v[78:79], v[126:127]
	v_fmac_f32_dpp v224, v76, v112 row_shr:1 row_mask:0xf bank_mask:0xf
	v_fmac_f32_dpp v225, v77, v113 row_shr:1 row_mask:0xf bank_mask:0xf
	v_fmac_f32_dpp v226, v78, v114 row_shr:1 row_mask:0xf bank_mask:0xf
	v_fmac_f32_dpp v227, v79, v115 row_shr:1 row_mask:0xf bank_mask:0xf
	v_fmac_f32_dpp v224, v84, v112 row_shl:15 row_mask:0xf bank_mask:0xf
	v_fmac_f32_dpp v225, v85, v113 row_shl:15 row_mask:0xf bank_mask:0xf
	v_fmac_f32_dpp v226, v86, v114 row_shl:15 row_mask:0xf bank_mask:0xf
	v_fmac_f32_dpp v227, v87, v115 row_shl:15 row_mask:0xf bank_mask:0xf
	v_fmac_f32_dpp v224, v76, v120 row_shl:1 row_mask:0xf bank_mask:0xf
	v_fmac_f32_dpp v225, v77, v121 row_shl:1 row_mask:0xf bank_mask:0xf
	v_fmac_f32_dpp v226, v78, v122 row_shl:1 row_mask:0xf bank_mask:0xf
	v_fmac_f32_dpp v227, v79, v123 row_shl:1 row_mask:0xf bank_mask:0xf
	v_fmac_f32_dpp v224, v68, v120 row_shr:15 row_mask:0xf bank_mask:0xf
	v_fmac_f32_dpp v225, v69, v121 row_shr:15 row_mask:0xf bank_mask:0xf
	v_fmac_f32_dpp v226, v70, v122 row_shr:15 row_mask:0xf bank_mask:0xf
	v_fmac_f32_dpp v227, v71, v123 row_shr:15 row_mask:0xf bank_mask:0xf
	v_pk_fma_f32 v[228:229], v[136:137], v[72:73], v[144:145]
	v_pk_fma_f32 v[230:231], v[138:139], v[74:75], v[146:147]
	v_fmac_f32_dpp v228, v72, v132 row_shr:1 row_mask:0xf bank_mask:0xf
	v_fmac_f32_dpp v229, v73, v133 row_shr:1 row_mask:0xf bank_mask:0xf
	v_fmac_f32_dpp v230, v74, v134 row_shr:1 row_mask:0xf bank_mask:0xf
	v_fmac_f32_dpp v231, v75, v135 row_shr:1 row_mask:0xf bank_mask:0xf
	v_fmac_f32_dpp v228, v80, v132 row_shl:15 row_mask:0xf bank_mask:0xf
	v_fmac_f32_dpp v229, v81, v133 row_shl:15 row_mask:0xf bank_mask:0xf
	v_fmac_f32_dpp v230, v82, v134 row_shl:15 row_mask:0xf bank_mask:0xf
	v_fmac_f32_dpp v231, v83, v135 row_shl:15 row_mask:0xf bank_mask:0xf
	v_fmac_f32_dpp v228, v72, v140 row_shl:1 row_mask:0xf bank_mask:0xf
	v_fmac_f32_dpp v229, v73, v141 row_shl:1 row_mask:0xf bank_mask:0xf
	v_fmac_f32_dpp v230, v74, v142 row_shl:1 row_mask:0xf bank_mask:0xf
	v_fmac_f32_dpp v231, v75, v143 row_shl:1 row_mask:0xf bank_mask:0xf
	v_fmac_f32_dpp v228, v64, v140 row_shr:15 row_mask:0xf bank_mask:0xf
	v_fmac_f32_dpp v229, v65, v141 row_shr:15 row_mask:0xf bank_mask:0xf
	v_fmac_f32_dpp v230, v66, v142 row_shr:15 row_mask:0xf bank_mask:0xf
	v_fmac_f32_dpp v231, v67, v143 row_shr:15 row_mask:0xf bank_mask:0xf
	v_pk_mul_f32 v[232:233], v[224:225], v[238:239]
	v_pk_mul_f32 v[234:235], v[226:227], v[238:239]
	v_exp_f32_e32 v232, v232
	v_exp_f32_e32 v233, v233
	v_exp_f32_e32 v234, v234
	v_exp_f32_e32 v235, v235
	v_pk_add_f32 v[232:233], v[232:233], 1.0 op_sel_hi:[1,0]
	v_pk_add_f32 v[234:235], v[234:235], 1.0 op_sel_hi:[1,0]
	v_rcp_f32_e32 v232, v232
	v_rcp_f32_e32 v233, v233
	v_rcp_f32_e32 v234, v234
	v_rcp_f32_e32 v235, v235
	v_pk_mul_f32 v[224:225], v[224:225], v[232:233]
	v_pk_mul_f32 v[226:227], v[226:227], v[234:235]
	v_pk_mul_f32 v[224:225], v[224:225], v[228:229]
	v_pk_mul_f32 v[226:227], v[226:227], v[230:231]
	v_cvt_pk_bf16_f32 v244, v224, v225
	v_cvt_pk_bf16_f32 v245, v226, v227
	v_pk_fma_f32 v[224:225], v[180:181], v[12:13], v[188:189]
	v_pk_fma_f32 v[226:227], v[182:183], v[14:15], v[190:191]
	v_fmac_f32_dpp v224, v12, v176 row_shr:1 row_mask:0xf bank_mask:0xf
	v_fmac_f32_dpp v225, v13, v177 row_shr:1 row_mask:0xf bank_mask:0xf
	v_fmac_f32_dpp v226, v14, v178 row_shr:1 row_mask:0xf bank_mask:0xf
	v_fmac_f32_dpp v227, v15, v179 row_shr:1 row_mask:0xf bank_mask:0xf
	v_fmac_f32_dpp v224, v20, v176 row_shl:15 row_mask:0xf bank_mask:0xf
	v_fmac_f32_dpp v225, v21, v177 row_shl:15 row_mask:0xf bank_mask:0xf
	v_fmac_f32_dpp v226, v22, v178 row_shl:15 row_mask:0xf bank_mask:0xf
	v_fmac_f32_dpp v227, v23, v179 row_shl:15 row_mask:0xf bank_mask:0xf
	v_fmac_f32_dpp v224, v12, v184 row_shl:1 row_mask:0xf bank_mask:0xf
	v_fmac_f32_dpp v225, v13, v185 row_shl:1 row_mask:0xf bank_mask:0xf
	v_fmac_f32_dpp v226, v14, v186 row_shl:1 row_mask:0xf bank_mask:0xf
	v_fmac_f32_dpp v227, v15, v187 row_shl:1 row_mask:0xf bank_mask:0xf
	v_fmac_f32_dpp v224, v4, v184 row_shr:15 row_mask:0xf bank_mask:0xf
	v_fmac_f32_dpp v225, v5, v185 row_shr:15 row_mask:0xf bank_mask:0xf
	v_fmac_f32_dpp v226, v6, v186 row_shr:15 row_mask:0xf bank_mask:0xf
	v_fmac_f32_dpp v227, v7, v187 row_shr:15 row_mask:0xf bank_mask:0xf
	v_pk_fma_f32 v[228:229], v[196:197], v[8:9], v[204:205]
	v_pk_fma_f32 v[230:231], v[198:199], v[10:11], v[206:207]
	v_fmac_f32_dpp v228, v8, v192 row_shr:1 row_mask:0xf bank_mask:0xf
	v_fmac_f32_dpp v229, v9, v193 row_shr:1 row_mask:0xf bank_mask:0xf
	v_fmac_f32_dpp v230, v10, v194 row_shr:1 row_mask:0xf bank_mask:0xf
	v_fmac_f32_dpp v231, v11, v195 row_shr:1 row_mask:0xf bank_mask:0xf
	v_fmac_f32_dpp v228, v16, v192 row_shl:15 row_mask:0xf bank_mask:0xf
	v_fmac_f32_dpp v229, v17, v193 row_shl:15 row_mask:0xf bank_mask:0xf
	v_fmac_f32_dpp v230, v18, v194 row_shl:15 row_mask:0xf bank_mask:0xf
	v_fmac_f32_dpp v231, v19, v195 row_shl:15 row_mask:0xf bank_mask:0xf
	v_fmac_f32_dpp v228, v8, v200 row_shl:1 row_mask:0xf bank_mask:0xf
	v_fmac_f32_dpp v229, v9, v201 row_shl:1 row_mask:0xf bank_mask:0xf
	v_fmac_f32_dpp v230, v10, v202 row_shl:1 row_mask:0xf bank_mask:0xf
	v_fmac_f32_dpp v231, v11, v203 row_shl:1 row_mask:0xf bank_mask:0xf
	v_fmac_f32_dpp v228, v0, v200 row_shr:15 row_mask:0xf bank_mask:0xf
	v_fmac_f32_dpp v229, v1, v201 row_shr:15 row_mask:0xf bank_mask:0xf
	v_fmac_f32_dpp v230, v2, v202 row_shr:15 row_mask:0xf bank_mask:0xf
	v_fmac_f32_dpp v231, v3, v203 row_shr:15 row_mask:0xf bank_mask:0xf
	v_pk_mul_f32 v[232:233], v[224:225], v[238:239]
	v_pk_mul_f32 v[234:235], v[226:227], v[238:239]
	v_exp_f32_e32 v232, v232
	v_exp_f32_e32 v233, v233
	v_exp_f32_e32 v234, v234
	v_exp_f32_e32 v235, v235
	v_pk_add_f32 v[232:233], v[232:233], 1.0 op_sel_hi:[1,0]
	v_pk_add_f32 v[234:235], v[234:235], 1.0 op_sel_hi:[1,0]
	v_rcp_f32_e32 v232, v232
	v_rcp_f32_e32 v233, v233
	v_rcp_f32_e32 v234, v234
	v_rcp_f32_e32 v235, v235
	v_pk_mul_f32 v[224:225], v[224:225], v[232:233]
	v_pk_mul_f32 v[226:227], v[226:227], v[234:235]
	v_pk_mul_f32 v[224:225], v[224:225], v[228:229]
	v_pk_mul_f32 v[226:227], v[226:227], v[230:231]
	v_cvt_pk_bf16_f32 v246, v224, v225
	v_cvt_pk_bf16_f32 v247, v226, v227
	v_add_u32_e32 v213, 0xdc000, v210
	global_store_dwordx4 v213, v[244:247], s[36:37]
	v_pk_fma_f32 v[224:225], v[116:117], v[68:69], v[124:125]
	v_pk_fma_f32 v[226:227], v[118:119], v[70:71], v[126:127]
	v_fmac_f32_dpp v224, v68, v112 row_shr:1 row_mask:0xf bank_mask:0xf
	v_fmac_f32_dpp v225, v69, v113 row_shr:1 row_mask:0xf bank_mask:0xf
	v_fmac_f32_dpp v226, v70, v114 row_shr:1 row_mask:0xf bank_mask:0xf
	v_fmac_f32_dpp v227, v71, v115 row_shr:1 row_mask:0xf bank_mask:0xf
	v_fmac_f32_dpp v224, v76, v112 row_shl:15 row_mask:0xf bank_mask:0xf
	v_fmac_f32_dpp v225, v77, v113 row_shl:15 row_mask:0xf bank_mask:0xf
	v_fmac_f32_dpp v226, v78, v114 row_shl:15 row_mask:0xf bank_mask:0xf
	v_fmac_f32_dpp v227, v79, v115 row_shl:15 row_mask:0xf bank_mask:0xf
	v_fmac_f32_dpp v224, v68, v120 row_shl:1 row_mask:0xf bank_mask:0xf
	v_fmac_f32_dpp v225, v69, v121 row_shl:1 row_mask:0xf bank_mask:0xf
	v_fmac_f32_dpp v226, v70, v122 row_shl:1 row_mask:0xf bank_mask:0xf
	v_fmac_f32_dpp v227, v71, v123 row_shl:1 row_mask:0xf bank_mask:0xf
	v_pk_fma_f32 v[228:229], v[136:137], v[64:65], v[144:145]
	v_pk_fma_f32 v[230:231], v[138:139], v[66:67], v[146:147]
	v_fmac_f32_dpp v228, v64, v132 row_shr:1 row_mask:0xf bank_mask:0xf
	v_fmac_f32_dpp v229, v65, v133 row_shr:1 row_mask:0xf bank_mask:0xf
	v_fmac_f32_dpp v230, v66, v134 row_shr:1 row_mask:0xf bank_mask:0xf
	v_fmac_f32_dpp v231, v67, v135 row_shr:1 row_mask:0xf bank_mask:0xf
	v_fmac_f32_dpp v228, v72, v132 row_shl:15 row_mask:0xf bank_mask:0xf
	v_fmac_f32_dpp v229, v73, v133 row_shl:15 row_mask:0xf bank_mask:0xf
	v_fmac_f32_dpp v230, v74, v134 row_shl:15 row_mask:0xf bank_mask:0xf
	v_fmac_f32_dpp v231, v75, v135 row_shl:15 row_mask:0xf bank_mask:0xf
	v_fmac_f32_dpp v228, v64, v140 row_shl:1 row_mask:0xf bank_mask:0xf
	v_fmac_f32_dpp v229, v65, v141 row_shl:1 row_mask:0xf bank_mask:0xf
	v_fmac_f32_dpp v230, v66, v142 row_shl:1 row_mask:0xf bank_mask:0xf
	v_fmac_f32_dpp v231, v67, v143 row_shl:1 row_mask:0xf bank_mask:0xf
	v_pk_mul_f32 v[232:233], v[224:225], v[238:239]
	v_pk_mul_f32 v[234:235], v[226:227], v[238:239]
	v_exp_f32_e32 v232, v232
	v_exp_f32_e32 v233, v233
	v_exp_f32_e32 v234, v234
	v_exp_f32_e32 v235, v235
	v_pk_add_f32 v[232:233], v[232:233], 1.0 op_sel_hi:[1,0]
	v_pk_add_f32 v[234:235], v[234:235], 1.0 op_sel_hi:[1,0]
	v_rcp_f32_e32 v232, v232
	v_rcp_f32_e32 v233, v233
	v_rcp_f32_e32 v234, v234
	v_rcp_f32_e32 v235, v235
	v_pk_mul_f32 v[224:225], v[224:225], v[232:233]
	v_pk_mul_f32 v[226:227], v[226:227], v[234:235]
	v_pk_mul_f32 v[224:225], v[224:225], v[228:229]
	v_pk_mul_f32 v[226:227], v[226:227], v[230:231]
	v_cvt_pk_bf16_f32 v244, v224, v225
	v_cvt_pk_bf16_f32 v245, v226, v227
	v_pk_fma_f32 v[224:225], v[180:181], v[4:5], v[188:189]
	v_pk_fma_f32 v[226:227], v[182:183], v[6:7], v[190:191]
	v_fmac_f32_dpp v224, v4, v176 row_shr:1 row_mask:0xf bank_mask:0xf
	v_fmac_f32_dpp v225, v5, v177 row_shr:1 row_mask:0xf bank_mask:0xf
	v_fmac_f32_dpp v226, v6, v178 row_shr:1 row_mask:0xf bank_mask:0xf
	v_fmac_f32_dpp v227, v7, v179 row_shr:1 row_mask:0xf bank_mask:0xf
	v_fmac_f32_dpp v224, v12, v176 row_shl:15 row_mask:0xf bank_mask:0xf
	v_fmac_f32_dpp v225, v13, v177 row_shl:15 row_mask:0xf bank_mask:0xf
	v_fmac_f32_dpp v226, v14, v178 row_shl:15 row_mask:0xf bank_mask:0xf
	v_fmac_f32_dpp v227, v15, v179 row_shl:15 row_mask:0xf bank_mask:0xf
	v_fmac_f32_dpp v224, v4, v184 row_shl:1 row_mask:0xf bank_mask:0xf
	v_fmac_f32_dpp v225, v5, v185 row_shl:1 row_mask:0xf bank_mask:0xf
	v_fmac_f32_dpp v226, v6, v186 row_shl:1 row_mask:0xf bank_mask:0xf
	v_fmac_f32_dpp v227, v7, v187 row_shl:1 row_mask:0xf bank_mask:0xf
	v_pk_fma_f32 v[228:229], v[196:197], v[0:1], v[204:205]
	v_pk_fma_f32 v[230:231], v[198:199], v[2:3], v[206:207]
	v_fmac_f32_dpp v228, v0, v192 row_shr:1 row_mask:0xf bank_mask:0xf
	v_fmac_f32_dpp v229, v1, v193 row_shr:1 row_mask:0xf bank_mask:0xf
	v_fmac_f32_dpp v230, v2, v194 row_shr:1 row_mask:0xf bank_mask:0xf
	v_fmac_f32_dpp v231, v3, v195 row_shr:1 row_mask:0xf bank_mask:0xf
	v_fmac_f32_dpp v228, v8, v192 row_shl:15 row_mask:0xf bank_mask:0xf
	v_fmac_f32_dpp v229, v9, v193 row_shl:15 row_mask:0xf bank_mask:0xf
	v_fmac_f32_dpp v230, v10, v194 row_shl:15 row_mask:0xf bank_mask:0xf
	v_fmac_f32_dpp v231, v11, v195 row_shl:15 row_mask:0xf bank_mask:0xf
	v_fmac_f32_dpp v228, v0, v200 row_shl:1 row_mask:0xf bank_mask:0xf
	v_fmac_f32_dpp v229, v1, v201 row_shl:1 row_mask:0xf bank_mask:0xf
	v_fmac_f32_dpp v230, v2, v202 row_shl:1 row_mask:0xf bank_mask:0xf
	v_fmac_f32_dpp v231, v3, v203 row_shl:1 row_mask:0xf bank_mask:0xf
	v_pk_mul_f32 v[232:233], v[224:225], v[238:239]
	v_pk_mul_f32 v[234:235], v[226:227], v[238:239]
	v_exp_f32_e32 v232, v232
	v_exp_f32_e32 v233, v233
	v_exp_f32_e32 v234, v234
	v_exp_f32_e32 v235, v235
	v_pk_add_f32 v[232:233], v[232:233], 1.0 op_sel_hi:[1,0]
	v_pk_add_f32 v[234:235], v[234:235], 1.0 op_sel_hi:[1,0]
	v_rcp_f32_e32 v232, v232
	v_rcp_f32_e32 v233, v233
	v_rcp_f32_e32 v234, v234
	v_rcp_f32_e32 v235, v235
	v_pk_mul_f32 v[224:225], v[224:225], v[232:233]
	v_pk_mul_f32 v[226:227], v[226:227], v[234:235]
	v_pk_mul_f32 v[224:225], v[224:225], v[228:229]
	v_pk_mul_f32 v[226:227], v[226:227], v[230:231]
	v_cvt_pk_bf16_f32 v246, v224, v225
	v_cvt_pk_bf16_f32 v247, v226, v227
	v_add_u32_e32 v213, 0xf2000, v210
	global_store_dwordx4 v213, v[244:247], s[36:37]
	s_andn2_b64 vcc, exec, s[10:11]
	s_mov_b64 s[2:3], -1
	s_cbranch_vccnz .LBB0_1180
	s_andn2_b64 vcc, exec, s[96:97]
	s_cbranch_vccnz .LBB0_1179
	s_barrier
	s_branch .LBB0_1179
